# FF1 as fused 128x256 tile pairs sharing the A tile: BK=64, A double-buffered, B0/B1 single-buffered and refilled behind mid-step barriers; second tile accumulators parked in free VGPRs until its epilo
# speedup vs baseline: 1.0162x; 1.0162x over previous
.LBB0_142:
	s_and_b64 vcc, exec, s[2:3]
	s_cbranch_vccz .LBB0_146
	s_lshr_b32 s9, s6, 1
	s_mul_i32 s9, s9, s90
	v_readlane_b32 s0, v247, 0
	s_add_i32 s9, s9, s0
	s_lshl_b32 s9, s9, 1
	s_and_b32 s0, s6, 1
	s_or_b32 s9, s9, s0
	v_readlane_b32 s0, v245, 43
	s_mov_b64 s[4:5], 0
	s_cmp_lt_i32 s9, s0
	s_mov_b64 s[0:1], 0
	s_cbranch_scc0 .LBB0_145
	s_ashr_i32 s0, s9, 31
	v_readlane_b32 s1, v244, 57
	s_xor_b32 s0, s0, s1
	s_abs_i32 s1, s9
	v_readlane_b32 s7, v244, 51
	s_mul_hi_u32 s7, s1, s7
	v_readlane_b32 s11, v244, 50
	s_mul_i32 s8, s7, s11
	s_sub_i32 s1, s1, s8
	s_add_i32 s8, s7, 1
	s_sub_i32 s10, s1, s11
	s_cmp_ge_u32 s1, s11
	s_cselect_b32 s7, s8, s7
	s_cselect_b32 s1, s10, s1
	s_add_i32 s8, s7, 1
	s_cmp_ge_u32 s1, s11
	s_cselect_b32 s1, s8, s7
	s_xor_b32 s1, s1, s0
	s_sub_i32 s0, s1, s0
	s_min_i32 s0, s0, 4
	v_readlane_b32 s1, v244, 56
	s_mul_i32 s1, s0, s1
	s_sub_i32 s1, s9, s1
	s_ashr_i32 s7, s1, 31
	s_lshr_b32 s7, s7, 29
	s_add_i32 s8, s1, s7
	s_ashr_i32 s7, s8, 3
	s_and_b32 s8, s8, -8
	v_readlane_b32 s9, v245, 42
	s_lshl_b32 s0, s0, 3
	s_sub_i32 s1, s1, s8
	s_add_i32 s7, s7, s9
	s_add_i32 s8, s1, s0
	s_mov_b64 s[0:1], -1

.LBB0_147:
	v_readlane_b32 s4, v243, 29
	s_lshr_b32 s5, s6, 1
	s_mul_i32 s4, s5, s4
	s_add_i32 s4, s4, s68
	s_lshl_b32 s4, s4, 1
	s_and_b32 s5, s6, 1
	s_or_b32 s4, s4, s5
	s_cmpk_lt_i32 s4, 0xc00
	v_readlane_b32 s5, v243, 30
	s_cbranch_scc0 .LBB0_149
	s_ashr_i32 s0, s4, 31
	s_lshr_b32 s0, s0, 27
	s_add_i32 s0, s4, s0
	s_ashr_i32 s7, s0, 5
	s_andn2_b32 s0, s0, 31
	s_sub_i32 s8, s4, s0
	s_mov_b64 s[0:1], -1
.LBB0_149:
	s_mov_b64 s[4:5], -1
	s_and_b64 vcc, exec, s[0:1]
	s_cbranch_vccz .LBB0_141
	v_mov_b32_e32 v69, v139
	v_ashrrev_i32_e32 v72, 6, v69
	v_bfe_u32 v68, v69, 3, 3
	v_bfe_u32 v71, v69, 4, 2
	v_and_b32_e32 v73, 15, v69
	v_ashrrev_i32_e32 v64, 1, v69
	v_and_b32_e32 v70, 0xffffffc0, v64
	s_lshl_b32 s1, s7, 7
	s_lshl_b32 s0, s8, 7
	s_bitcmp1_b32 s6, 0
	s_cbranch_scc1 ff1g_odd
	v_lshrrev_b32_e32 v66, 3, v69
	v_lshrrev_b32_e32 v67, 1, v66
	v_xor_b32_e32 v67, v67, v69
	v_and_b32_e32 v67, 7, v67
	v_lshlrev_b32_e32 v67, 4, v67
	s_movk_i32 s7, 0x880
	v_mad_u32_u24 v66, v66, s7, v67
	v_mov_b32_e32 v67, 0
	v_lshrrev_b32_e32 v64, 1, v69
	v_and_b32_e32 v64, 7, v64
	v_xor_b32_e32 v65, v64, v71
	v_lshlrev_b32_e32 v65, 4, v65
	v_or_b32_e32 v136, 4, v71
	v_xor_b32_e32 v136, v136, v64
	v_lshlrev_b32_e32 v136, 4, v136
	v_or_b32_e32 v64, v70, v73
	v_lshl_or_b32 v74, v64, 7, v65
	v_lshl_or_b32 v75, v64, 7, v136
	v_and_b32_e32 v64, 64, v69
	v_or_b32_e32 v64, v64, v73
	v_lshl_or_b32 v150, v64, 7, v65
	v_lshl_or_b32 v151, v64, 7, v136
	v_readfirstlane_b32 s4, v72
	v_readlane_b32 s50, v246, 23
	v_readlane_b32 s51, v246, 24
	v_readlane_b32 s48, v246, 9
	v_readlane_b32 s49, v246, 10
	s_lshl_b32 s10, s4, 10
	s_mul_i32 s9, s1, s7
	s_add_u32 s36, s50, s9
	s_addc_u32 s37, s51, 0
	v_lshl_add_u64 v[64:65], s[36:37], 0, v[66:67]
	s_mul_i32 s9, s0, s7
	s_add_u32 s36, s48, s9
	s_addc_u32 s37, s49, 0
	v_lshl_add_u64 v[66:67], s[36:37], 0, v[66:67]
	s_mov_b64 s[8:9], 0x80
	s_mov_b64 s[36:37], 0x11000
	s_mov_b64 s[38:39], 0x22000
	s_mov_b64 s[40:41], 0x33000
	s_mov_b64 s[42:43], 0x43f80
	s_mov_b64 s[44:45], 0x54f80
	s_mov_b64 s[46:47], 0x65f80
	s_mov_b64 s[48:49], 0x76f80
	s_add_u32 m0, s10, 0x0
	s_nop 0
	global_load_lds_dwordx4 v[64:65], off
	s_add_u32 m0, s10, 0x1000
	v_lshl_add_u64 v[152:153], v[64:65], 0, s[36:37]
	global_load_lds_dwordx4 v[152:153], off
	s_add_u32 m0, s10, 0x2000
	v_lshl_add_u64 v[152:153], v[64:65], 0, s[38:39]
	global_load_lds_dwordx4 v[152:153], off
	s_add_u32 m0, s10, 0x3000
	v_lshl_add_u64 v[152:153], v[64:65], 0, s[40:41]
	global_load_lds_dwordx4 v[152:153], off
	v_lshl_add_u64 v[64:65], v[64:65], 0, s[8:9]
	s_add_u32 m0, s10, 0x8000
	s_nop 0
	global_load_lds_dwordx4 v[66:67], off
	s_add_u32 m0, s10, 0x9000
	v_lshl_add_u64 v[152:153], v[66:67], 0, s[36:37]
	global_load_lds_dwordx4 v[152:153], off
	s_add_u32 m0, s10, 0xa000
	v_lshl_add_u64 v[152:153], v[66:67], 0, s[38:39]
	global_load_lds_dwordx4 v[152:153], off
	s_add_u32 m0, s10, 0xb000
	v_lshl_add_u64 v[152:153], v[66:67], 0, s[40:41]
	global_load_lds_dwordx4 v[152:153], off
	v_lshl_add_u64 v[66:67], v[66:67], 0, s[8:9]
	v_mov_b32_e32 v0, 0
	v_mov_b32_e32 v1, v0
	v_mov_b32_e32 v2, v0
	v_mov_b32_e32 v3, v0
	v_mov_b32_e32 v4, v0
	v_mov_b32_e32 v5, v0
	v_mov_b32_e32 v6, v0
	v_mov_b32_e32 v7, v0
	v_mov_b32_e32 v8, v0
	v_mov_b32_e32 v9, v0
	v_mov_b32_e32 v10, v0
	v_mov_b32_e32 v11, v0
	v_mov_b32_e32 v12, v0
	v_mov_b32_e32 v13, v0
	v_mov_b32_e32 v14, v0
	v_mov_b32_e32 v15, v0
	v_mov_b32_e32 v16, v0
	v_mov_b32_e32 v17, v0
	v_mov_b32_e32 v18, v0
	v_mov_b32_e32 v19, v0
	v_mov_b32_e32 v20, v0
	v_mov_b32_e32 v21, v0
	v_mov_b32_e32 v22, v0
	v_mov_b32_e32 v23, v0
	v_mov_b32_e32 v24, v0
	v_mov_b32_e32 v25, v0
	v_mov_b32_e32 v26, v0
	v_mov_b32_e32 v27, v0
	v_mov_b32_e32 v28, v0
	v_mov_b32_e32 v29, v0
	v_mov_b32_e32 v30, v0
	v_mov_b32_e32 v31, v0
	v_mov_b32_e32 v32, v0
	v_mov_b32_e32 v33, v0
	v_mov_b32_e32 v34, v0
	v_mov_b32_e32 v35, v0
	v_mov_b32_e32 v36, v0
	v_mov_b32_e32 v37, v0
	v_mov_b32_e32 v38, v0
	v_mov_b32_e32 v39, v0
	v_mov_b32_e32 v40, v0
	v_mov_b32_e32 v41, v0
	v_mov_b32_e32 v42, v0
	v_mov_b32_e32 v43, v0
	v_mov_b32_e32 v44, v0
	v_mov_b32_e32 v45, v0
	v_mov_b32_e32 v46, v0
	v_mov_b32_e32 v47, v0
	v_mov_b32_e32 v48, v0
	v_mov_b32_e32 v49, v0
	v_mov_b32_e32 v50, v0
	v_mov_b32_e32 v51, v0
	v_mov_b32_e32 v52, v0
	v_mov_b32_e32 v53, v0
	v_mov_b32_e32 v54, v0
	v_mov_b32_e32 v55, v0
	v_mov_b32_e32 v56, v0
	v_mov_b32_e32 v57, v0
	v_mov_b32_e32 v58, v0
	v_mov_b32_e32 v59, v0
	v_mov_b32_e32 v60, v0
	v_mov_b32_e32 v61, v0
	v_mov_b32_e32 v62, v0
	v_mov_b32_e32 v63, v0
	v_mov_b32_e32 v202, v0
	v_mov_b32_e32 v203, v0
	v_mov_b32_e32 v204, v0
	v_mov_b32_e32 v205, v0
	v_mov_b32_e32 v206, v0
	v_mov_b32_e32 v207, v0
	v_mov_b32_e32 v208, v0
	v_mov_b32_e32 v209, v0
	v_mov_b32_e32 v210, v0
	v_mov_b32_e32 v211, v0
	v_mov_b32_e32 v212, v0
	v_mov_b32_e32 v213, v0
	v_mov_b32_e32 v214, v0
	v_mov_b32_e32 v215, v0
	v_mov_b32_e32 v216, v0
	v_mov_b32_e32 v217, v0
	v_mov_b32_e32 v218, v0
	v_mov_b32_e32 v219, v0
	v_mov_b32_e32 v220, v0
	v_mov_b32_e32 v221, v0
	v_mov_b32_e32 v222, v0
	v_mov_b32_e32 v223, v0
	v_mov_b32_e32 v224, v0
	v_mov_b32_e32 v225, v0
	v_mov_b32_e32 v226, v0
	v_mov_b32_e32 v227, v0
	v_mov_b32_e32 v228, v0
	v_mov_b32_e32 v229, v0
	v_mov_b32_e32 v230, v0
	v_mov_b32_e32 v231, v0
	v_mov_b32_e32 v232, v0
	v_mov_b32_e32 v233, v0
	v_mov_b32_e32 v234, v0
	v_mov_b32_e32 v235, v0
	v_mov_b32_e32 v236, v0
	v_mov_b32_e32 v237, v0
	v_mov_b32_e32 v238, v0
	v_mov_b32_e32 v239, v0
	v_mov_b32_e32 v240, v0
	v_mov_b32_e32 v241, v0
	v_mov_b32_e32 v248, v0
	v_mov_b32_e32 v249, v0
	v_mov_b32_e32 v250, v0
	v_mov_b32_e32 v251, v0
	v_mov_b32_e32 v252, v0
	v_mov_b32_e32 v253, v0
	v_mov_b32_e32 v254, v0
	v_mov_b32_e32 v255, v0
	v_mov_b32_e32 v124, v0
	v_mov_b32_e32 v125, v0
	v_mov_b32_e32 v126, v0
	v_mov_b32_e32 v127, v0
	v_mov_b32_e32 v128, v0
	v_mov_b32_e32 v129, v0
	v_mov_b32_e32 v130, v0
	v_mov_b32_e32 v131, v0
	v_mov_b32_e32 v132, v0
	v_mov_b32_e32 v133, v0
	v_mov_b32_e32 v134, v0
	v_mov_b32_e32 v135, v0
	v_mov_b32_e32 v146, v0
	v_mov_b32_e32 v147, v0
	v_mov_b32_e32 v148, v0
	v_mov_b32_e32 v149, v0
	s_movk_i32 s11, 7
	s_waitcnt vmcnt(0)
	s_barrier
ff1g_loop:
	s_add_u32 m0, s10, 0xc000
	v_lshl_add_u64 v[152:153], v[66:67], 0, s[42:43]
	global_load_lds_dwordx4 v[152:153], off
	s_add_u32 m0, s10, 0xd000
	v_lshl_add_u64 v[152:153], v[66:67], 0, s[44:45]
	global_load_lds_dwordx4 v[152:153], off
	s_add_u32 m0, s10, 0xe000
	v_lshl_add_u64 v[152:153], v[66:67], 0, s[46:47]
	global_load_lds_dwordx4 v[152:153], off
	s_add_u32 m0, s10, 0xf000
	v_lshl_add_u64 v[152:153], v[66:67], 0, s[48:49]
	global_load_lds_dwordx4 v[152:153], off
	s_add_u32 m0, s10, 0x4000
	s_nop 0
	global_load_lds_dwordx4 v[64:65], off
	s_add_u32 m0, s10, 0x5000
	v_lshl_add_u64 v[152:153], v[64:65], 0, s[36:37]
	global_load_lds_dwordx4 v[152:153], off
	s_add_u32 m0, s10, 0x6000
	v_lshl_add_u64 v[152:153], v[64:65], 0, s[38:39]
	global_load_lds_dwordx4 v[152:153], off
	s_add_u32 m0, s10, 0x7000
	v_lshl_add_u64 v[152:153], v[64:65], 0, s[40:41]
	global_load_lds_dwordx4 v[152:153], off
	v_lshl_add_u64 v[64:65], v[64:65], 0, s[8:9]
	ds_read_b128 v[76:79], v74 offset:0
	ds_read_b128 v[80:83], v74 offset:2048
	ds_read_b128 v[84:87], v74 offset:4096
	ds_read_b128 v[88:91], v74 offset:6144
	ds_read_b128 v[108:111], v150 offset:32768
	ds_read_b128 v[112:115], v150 offset:34816
	ds_read_b128 v[116:119], v150 offset:36864
	ds_read_b128 v[120:123], v150 offset:38912
	ds_read_b128 v[92:95], v75 offset:0
	ds_read_b128 v[96:99], v75 offset:2048
	ds_read_b128 v[100:103], v75 offset:4096
	ds_read_b128 v[104:107], v75 offset:6144
	s_waitcnt lgkmcnt(4)
	v_mfma_f32_16x16x32_bf16 v[60:63], v[76:79], v[108:111], v[60:63]
	v_mfma_f32_16x16x32_bf16 v[56:59], v[76:79], v[112:115], v[56:59]
	v_mfma_f32_16x16x32_bf16 v[52:55], v[76:79], v[116:119], v[52:55]
	v_mfma_f32_16x16x32_bf16 v[48:51], v[76:79], v[120:123], v[48:51]
	v_mfma_f32_16x16x32_bf16 v[44:47], v[80:83], v[108:111], v[44:47]
	v_mfma_f32_16x16x32_bf16 v[40:43], v[80:83], v[112:115], v[40:43]
	v_mfma_f32_16x16x32_bf16 v[36:39], v[80:83], v[116:119], v[36:39]
	v_mfma_f32_16x16x32_bf16 v[32:35], v[80:83], v[120:123], v[32:35]
	v_mfma_f32_16x16x32_bf16 v[28:31], v[84:87], v[108:111], v[28:31]
	v_mfma_f32_16x16x32_bf16 v[24:27], v[84:87], v[112:115], v[24:27]
	v_mfma_f32_16x16x32_bf16 v[20:23], v[84:87], v[116:119], v[20:23]
	v_mfma_f32_16x16x32_bf16 v[16:19], v[84:87], v[120:123], v[16:19]
	v_mfma_f32_16x16x32_bf16 v[12:15], v[88:91], v[108:111], v[12:15]
	v_mfma_f32_16x16x32_bf16 v[8:11], v[88:91], v[112:115], v[8:11]
	v_mfma_f32_16x16x32_bf16 v[4:7], v[88:91], v[116:119], v[4:7]
	v_mfma_f32_16x16x32_bf16 v[0:3], v[88:91], v[120:123], v[0:3]
	ds_read_b128 v[108:111], v151 offset:32768
	ds_read_b128 v[112:115], v151 offset:34816
	ds_read_b128 v[116:119], v151 offset:36864
	ds_read_b128 v[120:123], v151 offset:38912
	s_waitcnt lgkmcnt(0)
	v_mfma_f32_16x16x32_bf16 v[60:63], v[92:95], v[108:111], v[60:63]
	v_mfma_f32_16x16x32_bf16 v[56:59], v[92:95], v[112:115], v[56:59]
	v_mfma_f32_16x16x32_bf16 v[52:55], v[92:95], v[116:119], v[52:55]
	v_mfma_f32_16x16x32_bf16 v[48:51], v[92:95], v[120:123], v[48:51]
	v_mfma_f32_16x16x32_bf16 v[44:47], v[96:99], v[108:111], v[44:47]
	v_mfma_f32_16x16x32_bf16 v[40:43], v[96:99], v[112:115], v[40:43]
	v_mfma_f32_16x16x32_bf16 v[36:39], v[96:99], v[116:119], v[36:39]
	v_mfma_f32_16x16x32_bf16 v[32:35], v[96:99], v[120:123], v[32:35]
	v_mfma_f32_16x16x32_bf16 v[28:31], v[100:103], v[108:111], v[28:31]
	v_mfma_f32_16x16x32_bf16 v[24:27], v[100:103], v[112:115], v[24:27]
	v_mfma_f32_16x16x32_bf16 v[20:23], v[100:103], v[116:119], v[20:23]
	v_mfma_f32_16x16x32_bf16 v[16:19], v[100:103], v[120:123], v[16:19]
	v_mfma_f32_16x16x32_bf16 v[12:15], v[104:107], v[108:111], v[12:15]
	v_mfma_f32_16x16x32_bf16 v[8:11], v[104:107], v[112:115], v[8:11]
	v_mfma_f32_16x16x32_bf16 v[4:7], v[104:107], v[116:119], v[4:7]
	v_mfma_f32_16x16x32_bf16 v[0:3], v[104:107], v[120:123], v[0:3]
	s_waitcnt vmcnt(4)
	s_barrier
	s_add_u32 m0, s10, 0x8000
	s_nop 0
	global_load_lds_dwordx4 v[66:67], off
	s_add_u32 m0, s10, 0x9000
	v_lshl_add_u64 v[152:153], v[66:67], 0, s[36:37]
	global_load_lds_dwordx4 v[152:153], off
	s_add_u32 m0, s10, 0xa000
	v_lshl_add_u64 v[152:153], v[66:67], 0, s[38:39]
	global_load_lds_dwordx4 v[152:153], off
	s_add_u32 m0, s10, 0xb000
	v_lshl_add_u64 v[152:153], v[66:67], 0, s[40:41]
	global_load_lds_dwordx4 v[152:153], off
	v_lshl_add_u64 v[66:67], v[66:67], 0, s[8:9]
	ds_read_b128 v[108:111], v150 offset:49152
	ds_read_b128 v[112:115], v150 offset:51200
	ds_read_b128 v[116:119], v150 offset:53248
	ds_read_b128 v[120:123], v150 offset:55296
	s_waitcnt lgkmcnt(0)
	v_mfma_f32_16x16x32_bf16 v[202:205], v[76:79], v[108:111], v[202:205]
	v_mfma_f32_16x16x32_bf16 v[206:209], v[76:79], v[112:115], v[206:209]
	v_mfma_f32_16x16x32_bf16 v[210:213], v[76:79], v[116:119], v[210:213]
	v_mfma_f32_16x16x32_bf16 v[214:217], v[76:79], v[120:123], v[214:217]
	v_mfma_f32_16x16x32_bf16 v[218:221], v[80:83], v[108:111], v[218:221]
	v_mfma_f32_16x16x32_bf16 v[222:225], v[80:83], v[112:115], v[222:225]
	v_mfma_f32_16x16x32_bf16 v[226:229], v[80:83], v[116:119], v[226:229]
	v_mfma_f32_16x16x32_bf16 v[230:233], v[80:83], v[120:123], v[230:233]
	v_mfma_f32_16x16x32_bf16 v[234:237], v[84:87], v[108:111], v[234:237]
	v_mfma_f32_16x16x32_bf16 v[238:241], v[84:87], v[112:115], v[238:241]
	v_mfma_f32_16x16x32_bf16 v[248:251], v[84:87], v[116:119], v[248:251]
	v_mfma_f32_16x16x32_bf16 v[252:255], v[84:87], v[120:123], v[252:255]
	v_mfma_f32_16x16x32_bf16 v[124:127], v[88:91], v[108:111], v[124:127]
	v_mfma_f32_16x16x32_bf16 v[128:131], v[88:91], v[112:115], v[128:131]
	v_mfma_f32_16x16x32_bf16 v[132:135], v[88:91], v[116:119], v[132:135]
	v_mfma_f32_16x16x32_bf16 v[146:149], v[88:91], v[120:123], v[146:149]
	ds_read_b128 v[108:111], v151 offset:49152
	ds_read_b128 v[112:115], v151 offset:51200
	ds_read_b128 v[116:119], v151 offset:53248
	ds_read_b128 v[120:123], v151 offset:55296
	s_waitcnt lgkmcnt(0)
	v_mfma_f32_16x16x32_bf16 v[202:205], v[92:95], v[108:111], v[202:205]
	v_mfma_f32_16x16x32_bf16 v[206:209], v[92:95], v[112:115], v[206:209]
	v_mfma_f32_16x16x32_bf16 v[210:213], v[92:95], v[116:119], v[210:213]
	v_mfma_f32_16x16x32_bf16 v[214:217], v[92:95], v[120:123], v[214:217]
	v_mfma_f32_16x16x32_bf16 v[218:221], v[96:99], v[108:111], v[218:221]
	v_mfma_f32_16x16x32_bf16 v[222:225], v[96:99], v[112:115], v[222:225]
	v_mfma_f32_16x16x32_bf16 v[226:229], v[96:99], v[116:119], v[226:229]
	v_mfma_f32_16x16x32_bf16 v[230:233], v[96:99], v[120:123], v[230:233]
	v_mfma_f32_16x16x32_bf16 v[234:237], v[100:103], v[108:111], v[234:237]
	v_mfma_f32_16x16x32_bf16 v[238:241], v[100:103], v[112:115], v[238:241]
	v_mfma_f32_16x16x32_bf16 v[248:251], v[100:103], v[116:119], v[248:251]
	v_mfma_f32_16x16x32_bf16 v[252:255], v[100:103], v[120:123], v[252:255]
	v_mfma_f32_16x16x32_bf16 v[124:127], v[104:107], v[108:111], v[124:127]
	v_mfma_f32_16x16x32_bf16 v[128:131], v[104:107], v[112:115], v[128:131]
	v_mfma_f32_16x16x32_bf16 v[132:135], v[104:107], v[116:119], v[132:135]
	v_mfma_f32_16x16x32_bf16 v[146:149], v[104:107], v[120:123], v[146:149]
	s_waitcnt vmcnt(0)
	s_barrier
	s_add_u32 m0, s10, 0xc000
	v_lshl_add_u64 v[152:153], v[66:67], 0, s[42:43]
	global_load_lds_dwordx4 v[152:153], off
	s_add_u32 m0, s10, 0xd000
	v_lshl_add_u64 v[152:153], v[66:67], 0, s[44:45]
	global_load_lds_dwordx4 v[152:153], off
	s_add_u32 m0, s10, 0xe000
	v_lshl_add_u64 v[152:153], v[66:67], 0, s[46:47]
	global_load_lds_dwordx4 v[152:153], off
	s_add_u32 m0, s10, 0xf000
	v_lshl_add_u64 v[152:153], v[66:67], 0, s[48:49]
	global_load_lds_dwordx4 v[152:153], off
	s_add_u32 m0, s10, 0x0
	s_nop 0
	global_load_lds_dwordx4 v[64:65], off
	s_add_u32 m0, s10, 0x1000
	v_lshl_add_u64 v[152:153], v[64:65], 0, s[36:37]
	global_load_lds_dwordx4 v[152:153], off
	s_add_u32 m0, s10, 0x2000
	v_lshl_add_u64 v[152:153], v[64:65], 0, s[38:39]
	global_load_lds_dwordx4 v[152:153], off
	s_add_u32 m0, s10, 0x3000
	v_lshl_add_u64 v[152:153], v[64:65], 0, s[40:41]
	global_load_lds_dwordx4 v[152:153], off
	v_lshl_add_u64 v[64:65], v[64:65], 0, s[8:9]
	ds_read_b128 v[76:79], v74 offset:16384
	ds_read_b128 v[80:83], v74 offset:18432
	ds_read_b128 v[84:87], v74 offset:20480
	ds_read_b128 v[88:91], v74 offset:22528
	ds_read_b128 v[108:111], v150 offset:32768
	ds_read_b128 v[112:115], v150 offset:34816
	ds_read_b128 v[116:119], v150 offset:36864
	ds_read_b128 v[120:123], v150 offset:38912
	ds_read_b128 v[92:95], v75 offset:16384
	ds_read_b128 v[96:99], v75 offset:18432
	ds_read_b128 v[100:103], v75 offset:20480
	ds_read_b128 v[104:107], v75 offset:22528
	s_waitcnt lgkmcnt(4)
	v_mfma_f32_16x16x32_bf16 v[60:63], v[76:79], v[108:111], v[60:63]
	v_mfma_f32_16x16x32_bf16 v[56:59], v[76:79], v[112:115], v[56:59]
	v_mfma_f32_16x16x32_bf16 v[52:55], v[76:79], v[116:119], v[52:55]
	v_mfma_f32_16x16x32_bf16 v[48:51], v[76:79], v[120:123], v[48:51]
	v_mfma_f32_16x16x32_bf16 v[44:47], v[80:83], v[108:111], v[44:47]
	v_mfma_f32_16x16x32_bf16 v[40:43], v[80:83], v[112:115], v[40:43]
	v_mfma_f32_16x16x32_bf16 v[36:39], v[80:83], v[116:119], v[36:39]
	v_mfma_f32_16x16x32_bf16 v[32:35], v[80:83], v[120:123], v[32:35]
	v_mfma_f32_16x16x32_bf16 v[28:31], v[84:87], v[108:111], v[28:31]
	v_mfma_f32_16x16x32_bf16 v[24:27], v[84:87], v[112:115], v[24:27]
	v_mfma_f32_16x16x32_bf16 v[20:23], v[84:87], v[116:119], v[20:23]
	v_mfma_f32_16x16x32_bf16 v[16:19], v[84:87], v[120:123], v[16:19]
	v_mfma_f32_16x16x32_bf16 v[12:15], v[88:91], v[108:111], v[12:15]
	v_mfma_f32_16x16x32_bf16 v[8:11], v[88:91], v[112:115], v[8:11]
	v_mfma_f32_16x16x32_bf16 v[4:7], v[88:91], v[116:119], v[4:7]
	v_mfma_f32_16x16x32_bf16 v[0:3], v[88:91], v[120:123], v[0:3]
	ds_read_b128 v[108:111], v151 offset:32768
	ds_read_b128 v[112:115], v151 offset:34816
	ds_read_b128 v[116:119], v151 offset:36864
	ds_read_b128 v[120:123], v151 offset:38912
	s_waitcnt lgkmcnt(0)
	v_mfma_f32_16x16x32_bf16 v[60:63], v[92:95], v[108:111], v[60:63]
	v_mfma_f32_16x16x32_bf16 v[56:59], v[92:95], v[112:115], v[56:59]
	v_mfma_f32_16x16x32_bf16 v[52:55], v[92:95], v[116:119], v[52:55]
	v_mfma_f32_16x16x32_bf16 v[48:51], v[92:95], v[120:123], v[48:51]
	v_mfma_f32_16x16x32_bf16 v[44:47], v[96:99], v[108:111], v[44:47]
	v_mfma_f32_16x16x32_bf16 v[40:43], v[96:99], v[112:115], v[40:43]
	v_mfma_f32_16x16x32_bf16 v[36:39], v[96:99], v[116:119], v[36:39]
	v_mfma_f32_16x16x32_bf16 v[32:35], v[96:99], v[120:123], v[32:35]
	v_mfma_f32_16x16x32_bf16 v[28:31], v[100:103], v[108:111], v[28:31]
	v_mfma_f32_16x16x32_bf16 v[24:27], v[100:103], v[112:115], v[24:27]
	v_mfma_f32_16x16x32_bf16 v[20:23], v[100:103], v[116:119], v[20:23]
	v_mfma_f32_16x16x32_bf16 v[16:19], v[100:103], v[120:123], v[16:19]
	v_mfma_f32_16x16x32_bf16 v[12:15], v[104:107], v[108:111], v[12:15]
	v_mfma_f32_16x16x32_bf16 v[8:11], v[104:107], v[112:115], v[8:11]
	v_mfma_f32_16x16x32_bf16 v[4:7], v[104:107], v[116:119], v[4:7]
	v_mfma_f32_16x16x32_bf16 v[0:3], v[104:107], v[120:123], v[0:3]
	s_waitcnt vmcnt(4)
	s_barrier
	s_add_u32 m0, s10, 0x8000
	s_nop 0
	global_load_lds_dwordx4 v[66:67], off
	s_add_u32 m0, s10, 0x9000
	v_lshl_add_u64 v[152:153], v[66:67], 0, s[36:37]
	global_load_lds_dwordx4 v[152:153], off
	s_add_u32 m0, s10, 0xa000
	v_lshl_add_u64 v[152:153], v[66:67], 0, s[38:39]
	global_load_lds_dwordx4 v[152:153], off
	s_add_u32 m0, s10, 0xb000
	v_lshl_add_u64 v[152:153], v[66:67], 0, s[40:41]
	global_load_lds_dwordx4 v[152:153], off
	v_lshl_add_u64 v[66:67], v[66:67], 0, s[8:9]
	ds_read_b128 v[108:111], v150 offset:49152
	ds_read_b128 v[112:115], v150 offset:51200
	ds_read_b128 v[116:119], v150 offset:53248
	ds_read_b128 v[120:123], v150 offset:55296
	s_waitcnt lgkmcnt(0)
	v_mfma_f32_16x16x32_bf16 v[202:205], v[76:79], v[108:111], v[202:205]
	v_mfma_f32_16x16x32_bf16 v[206:209], v[76:79], v[112:115], v[206:209]
	v_mfma_f32_16x16x32_bf16 v[210:213], v[76:79], v[116:119], v[210:213]
	v_mfma_f32_16x16x32_bf16 v[214:217], v[76:79], v[120:123], v[214:217]
	v_mfma_f32_16x16x32_bf16 v[218:221], v[80:83], v[108:111], v[218:221]
	v_mfma_f32_16x16x32_bf16 v[222:225], v[80:83], v[112:115], v[222:225]
	v_mfma_f32_16x16x32_bf16 v[226:229], v[80:83], v[116:119], v[226:229]
	v_mfma_f32_16x16x32_bf16 v[230:233], v[80:83], v[120:123], v[230:233]
	v_mfma_f32_16x16x32_bf16 v[234:237], v[84:87], v[108:111], v[234:237]
	v_mfma_f32_16x16x32_bf16 v[238:241], v[84:87], v[112:115], v[238:241]
	v_mfma_f32_16x16x32_bf16 v[248:251], v[84:87], v[116:119], v[248:251]
	v_mfma_f32_16x16x32_bf16 v[252:255], v[84:87], v[120:123], v[252:255]
	v_mfma_f32_16x16x32_bf16 v[124:127], v[88:91], v[108:111], v[124:127]
	v_mfma_f32_16x16x32_bf16 v[128:131], v[88:91], v[112:115], v[128:131]
	v_mfma_f32_16x16x32_bf16 v[132:135], v[88:91], v[116:119], v[132:135]
	v_mfma_f32_16x16x32_bf16 v[146:149], v[88:91], v[120:123], v[146:149]
	ds_read_b128 v[108:111], v151 offset:49152
	ds_read_b128 v[112:115], v151 offset:51200
	ds_read_b128 v[116:119], v151 offset:53248
	ds_read_b128 v[120:123], v151 offset:55296
	s_waitcnt lgkmcnt(0)
	v_mfma_f32_16x16x32_bf16 v[202:205], v[92:95], v[108:111], v[202:205]
	v_mfma_f32_16x16x32_bf16 v[206:209], v[92:95], v[112:115], v[206:209]
	v_mfma_f32_16x16x32_bf16 v[210:213], v[92:95], v[116:119], v[210:213]
	v_mfma_f32_16x16x32_bf16 v[214:217], v[92:95], v[120:123], v[214:217]
	v_mfma_f32_16x16x32_bf16 v[218:221], v[96:99], v[108:111], v[218:221]
	v_mfma_f32_16x16x32_bf16 v[222:225], v[96:99], v[112:115], v[222:225]
	v_mfma_f32_16x16x32_bf16 v[226:229], v[96:99], v[116:119], v[226:229]
	v_mfma_f32_16x16x32_bf16 v[230:233], v[96:99], v[120:123], v[230:233]
	v_mfma_f32_16x16x32_bf16 v[234:237], v[100:103], v[108:111], v[234:237]
	v_mfma_f32_16x16x32_bf16 v[238:241], v[100:103], v[112:115], v[238:241]
	v_mfma_f32_16x16x32_bf16 v[248:251], v[100:103], v[116:119], v[248:251]
	v_mfma_f32_16x16x32_bf16 v[252:255], v[100:103], v[120:123], v[252:255]
	v_mfma_f32_16x16x32_bf16 v[124:127], v[104:107], v[108:111], v[124:127]
	v_mfma_f32_16x16x32_bf16 v[128:131], v[104:107], v[112:115], v[128:131]
	v_mfma_f32_16x16x32_bf16 v[132:135], v[104:107], v[116:119], v[132:135]
	v_mfma_f32_16x16x32_bf16 v[146:149], v[104:107], v[120:123], v[146:149]
	s_waitcnt vmcnt(0)
	s_barrier
	s_sub_u32 s11, s11, 1
	s_cmp_lg_u32 s11, 0
	s_cbranch_scc1 ff1g_loop
	s_add_u32 m0, s10, 0xc000
	v_lshl_add_u64 v[152:153], v[66:67], 0, s[42:43]
	global_load_lds_dwordx4 v[152:153], off
	s_add_u32 m0, s10, 0xd000
	v_lshl_add_u64 v[152:153], v[66:67], 0, s[44:45]
	global_load_lds_dwordx4 v[152:153], off
	s_add_u32 m0, s10, 0xe000
	v_lshl_add_u64 v[152:153], v[66:67], 0, s[46:47]
	global_load_lds_dwordx4 v[152:153], off
	s_add_u32 m0, s10, 0xf000
	v_lshl_add_u64 v[152:153], v[66:67], 0, s[48:49]
	global_load_lds_dwordx4 v[152:153], off
	s_add_u32 m0, s10, 0x4000
	s_nop 0
	global_load_lds_dwordx4 v[64:65], off
	s_add_u32 m0, s10, 0x5000
	v_lshl_add_u64 v[152:153], v[64:65], 0, s[36:37]
	global_load_lds_dwordx4 v[152:153], off
	s_add_u32 m0, s10, 0x6000
	v_lshl_add_u64 v[152:153], v[64:65], 0, s[38:39]
	global_load_lds_dwordx4 v[152:153], off
	s_add_u32 m0, s10, 0x7000
	v_lshl_add_u64 v[152:153], v[64:65], 0, s[40:41]
	global_load_lds_dwordx4 v[152:153], off
	v_lshl_add_u64 v[64:65], v[64:65], 0, s[8:9]
	ds_read_b128 v[76:79], v74 offset:0
	ds_read_b128 v[80:83], v74 offset:2048
	ds_read_b128 v[84:87], v74 offset:4096
	ds_read_b128 v[88:91], v74 offset:6144
	ds_read_b128 v[108:111], v150 offset:32768
	ds_read_b128 v[112:115], v150 offset:34816
	ds_read_b128 v[116:119], v150 offset:36864
	ds_read_b128 v[120:123], v150 offset:38912
	ds_read_b128 v[92:95], v75 offset:0
	ds_read_b128 v[96:99], v75 offset:2048
	ds_read_b128 v[100:103], v75 offset:4096
	ds_read_b128 v[104:107], v75 offset:6144
	s_waitcnt lgkmcnt(4)
	v_mfma_f32_16x16x32_bf16 v[60:63], v[76:79], v[108:111], v[60:63]
	v_mfma_f32_16x16x32_bf16 v[56:59], v[76:79], v[112:115], v[56:59]
	v_mfma_f32_16x16x32_bf16 v[52:55], v[76:79], v[116:119], v[52:55]
	v_mfma_f32_16x16x32_bf16 v[48:51], v[76:79], v[120:123], v[48:51]
	v_mfma_f32_16x16x32_bf16 v[44:47], v[80:83], v[108:111], v[44:47]
	v_mfma_f32_16x16x32_bf16 v[40:43], v[80:83], v[112:115], v[40:43]
	v_mfma_f32_16x16x32_bf16 v[36:39], v[80:83], v[116:119], v[36:39]
	v_mfma_f32_16x16x32_bf16 v[32:35], v[80:83], v[120:123], v[32:35]
	v_mfma_f32_16x16x32_bf16 v[28:31], v[84:87], v[108:111], v[28:31]
	v_mfma_f32_16x16x32_bf16 v[24:27], v[84:87], v[112:115], v[24:27]
	v_mfma_f32_16x16x32_bf16 v[20:23], v[84:87], v[116:119], v[20:23]
	v_mfma_f32_16x16x32_bf16 v[16:19], v[84:87], v[120:123], v[16:19]
	v_mfma_f32_16x16x32_bf16 v[12:15], v[88:91], v[108:111], v[12:15]
	v_mfma_f32_16x16x32_bf16 v[8:11], v[88:91], v[112:115], v[8:11]
	v_mfma_f32_16x16x32_bf16 v[4:7], v[88:91], v[116:119], v[4:7]
	v_mfma_f32_16x16x32_bf16 v[0:3], v[88:91], v[120:123], v[0:3]
	ds_read_b128 v[108:111], v151 offset:32768
	ds_read_b128 v[112:115], v151 offset:34816
	ds_read_b128 v[116:119], v151 offset:36864
	ds_read_b128 v[120:123], v151 offset:38912
	s_waitcnt lgkmcnt(0)
	v_mfma_f32_16x16x32_bf16 v[60:63], v[92:95], v[108:111], v[60:63]
	v_mfma_f32_16x16x32_bf16 v[56:59], v[92:95], v[112:115], v[56:59]
	v_mfma_f32_16x16x32_bf16 v[52:55], v[92:95], v[116:119], v[52:55]
	v_mfma_f32_16x16x32_bf16 v[48:51], v[92:95], v[120:123], v[48:51]
	v_mfma_f32_16x16x32_bf16 v[44:47], v[96:99], v[108:111], v[44:47]
	v_mfma_f32_16x16x32_bf16 v[40:43], v[96:99], v[112:115], v[40:43]
	v_mfma_f32_16x16x32_bf16 v[36:39], v[96:99], v[116:119], v[36:39]
	v_mfma_f32_16x16x32_bf16 v[32:35], v[96:99], v[120:123], v[32:35]
	v_mfma_f32_16x16x32_bf16 v[28:31], v[100:103], v[108:111], v[28:31]
	v_mfma_f32_16x16x32_bf16 v[24:27], v[100:103], v[112:115], v[24:27]
	v_mfma_f32_16x16x32_bf16 v[20:23], v[100:103], v[116:119], v[20:23]
	v_mfma_f32_16x16x32_bf16 v[16:19], v[100:103], v[120:123], v[16:19]
	v_mfma_f32_16x16x32_bf16 v[12:15], v[104:107], v[108:111], v[12:15]
	v_mfma_f32_16x16x32_bf16 v[8:11], v[104:107], v[112:115], v[8:11]
	v_mfma_f32_16x16x32_bf16 v[4:7], v[104:107], v[116:119], v[4:7]
	v_mfma_f32_16x16x32_bf16 v[0:3], v[104:107], v[120:123], v[0:3]
	s_waitcnt vmcnt(4)
	s_barrier
	s_add_u32 m0, s10, 0x8000
	s_nop 0
	global_load_lds_dwordx4 v[66:67], off
	s_add_u32 m0, s10, 0x9000
	v_lshl_add_u64 v[152:153], v[66:67], 0, s[36:37]
	global_load_lds_dwordx4 v[152:153], off
	s_add_u32 m0, s10, 0xa000
	v_lshl_add_u64 v[152:153], v[66:67], 0, s[38:39]
	global_load_lds_dwordx4 v[152:153], off
	s_add_u32 m0, s10, 0xb000
	v_lshl_add_u64 v[152:153], v[66:67], 0, s[40:41]
	global_load_lds_dwordx4 v[152:153], off
	v_lshl_add_u64 v[66:67], v[66:67], 0, s[8:9]
	ds_read_b128 v[108:111], v150 offset:49152
	ds_read_b128 v[112:115], v150 offset:51200
	ds_read_b128 v[116:119], v150 offset:53248
	ds_read_b128 v[120:123], v150 offset:55296
	s_waitcnt lgkmcnt(0)
	v_mfma_f32_16x16x32_bf16 v[202:205], v[76:79], v[108:111], v[202:205]
	v_mfma_f32_16x16x32_bf16 v[206:209], v[76:79], v[112:115], v[206:209]
	v_mfma_f32_16x16x32_bf16 v[210:213], v[76:79], v[116:119], v[210:213]
	v_mfma_f32_16x16x32_bf16 v[214:217], v[76:79], v[120:123], v[214:217]
	v_mfma_f32_16x16x32_bf16 v[218:221], v[80:83], v[108:111], v[218:221]
	v_mfma_f32_16x16x32_bf16 v[222:225], v[80:83], v[112:115], v[222:225]
	v_mfma_f32_16x16x32_bf16 v[226:229], v[80:83], v[116:119], v[226:229]
	v_mfma_f32_16x16x32_bf16 v[230:233], v[80:83], v[120:123], v[230:233]
	v_mfma_f32_16x16x32_bf16 v[234:237], v[84:87], v[108:111], v[234:237]
	v_mfma_f32_16x16x32_bf16 v[238:241], v[84:87], v[112:115], v[238:241]
	v_mfma_f32_16x16x32_bf16 v[248:251], v[84:87], v[116:119], v[248:251]
	v_mfma_f32_16x16x32_bf16 v[252:255], v[84:87], v[120:123], v[252:255]
	v_mfma_f32_16x16x32_bf16 v[124:127], v[88:91], v[108:111], v[124:127]
	v_mfma_f32_16x16x32_bf16 v[128:131], v[88:91], v[112:115], v[128:131]
	v_mfma_f32_16x16x32_bf16 v[132:135], v[88:91], v[116:119], v[132:135]
	v_mfma_f32_16x16x32_bf16 v[146:149], v[88:91], v[120:123], v[146:149]
	ds_read_b128 v[108:111], v151 offset:49152
	ds_read_b128 v[112:115], v151 offset:51200
	ds_read_b128 v[116:119], v151 offset:53248
	ds_read_b128 v[120:123], v151 offset:55296
	s_waitcnt lgkmcnt(0)
	v_mfma_f32_16x16x32_bf16 v[202:205], v[92:95], v[108:111], v[202:205]
	v_mfma_f32_16x16x32_bf16 v[206:209], v[92:95], v[112:115], v[206:209]
	v_mfma_f32_16x16x32_bf16 v[210:213], v[92:95], v[116:119], v[210:213]
	v_mfma_f32_16x16x32_bf16 v[214:217], v[92:95], v[120:123], v[214:217]
	v_mfma_f32_16x16x32_bf16 v[218:221], v[96:99], v[108:111], v[218:221]
	v_mfma_f32_16x16x32_bf16 v[222:225], v[96:99], v[112:115], v[222:225]
	v_mfma_f32_16x16x32_bf16 v[226:229], v[96:99], v[116:119], v[226:229]
	v_mfma_f32_16x16x32_bf16 v[230:233], v[96:99], v[120:123], v[230:233]
	v_mfma_f32_16x16x32_bf16 v[234:237], v[100:103], v[108:111], v[234:237]
	v_mfma_f32_16x16x32_bf16 v[238:241], v[100:103], v[112:115], v[238:241]
	v_mfma_f32_16x16x32_bf16 v[248:251], v[100:103], v[116:119], v[248:251]
	v_mfma_f32_16x16x32_bf16 v[252:255], v[100:103], v[120:123], v[252:255]
	v_mfma_f32_16x16x32_bf16 v[124:127], v[104:107], v[108:111], v[124:127]
	v_mfma_f32_16x16x32_bf16 v[128:131], v[104:107], v[112:115], v[128:131]
	v_mfma_f32_16x16x32_bf16 v[132:135], v[104:107], v[116:119], v[132:135]
	v_mfma_f32_16x16x32_bf16 v[146:149], v[104:107], v[120:123], v[146:149]
	s_waitcnt vmcnt(0)
	s_barrier
	s_add_u32 m0, s10, 0xc000
	v_lshl_add_u64 v[152:153], v[66:67], 0, s[42:43]
	global_load_lds_dwordx4 v[152:153], off
	s_add_u32 m0, s10, 0xd000
	v_lshl_add_u64 v[152:153], v[66:67], 0, s[44:45]
	global_load_lds_dwordx4 v[152:153], off
	s_add_u32 m0, s10, 0xe000
	v_lshl_add_u64 v[152:153], v[66:67], 0, s[46:47]
	global_load_lds_dwordx4 v[152:153], off
	s_add_u32 m0, s10, 0xf000
	v_lshl_add_u64 v[152:153], v[66:67], 0, s[48:49]
	global_load_lds_dwordx4 v[152:153], off
	ds_read_b128 v[76:79], v74 offset:16384
	ds_read_b128 v[80:83], v74 offset:18432
	ds_read_b128 v[84:87], v74 offset:20480
	ds_read_b128 v[88:91], v74 offset:22528
	ds_read_b128 v[108:111], v150 offset:32768
	ds_read_b128 v[112:115], v150 offset:34816
	ds_read_b128 v[116:119], v150 offset:36864
	ds_read_b128 v[120:123], v150 offset:38912
	ds_read_b128 v[92:95], v75 offset:16384
	ds_read_b128 v[96:99], v75 offset:18432
	ds_read_b128 v[100:103], v75 offset:20480
	ds_read_b128 v[104:107], v75 offset:22528
	s_waitcnt lgkmcnt(4)
	v_mfma_f32_16x16x32_bf16 v[60:63], v[76:79], v[108:111], v[60:63]
	v_mfma_f32_16x16x32_bf16 v[56:59], v[76:79], v[112:115], v[56:59]
	v_mfma_f32_16x16x32_bf16 v[52:55], v[76:79], v[116:119], v[52:55]
	v_mfma_f32_16x16x32_bf16 v[48:51], v[76:79], v[120:123], v[48:51]
	v_mfma_f32_16x16x32_bf16 v[44:47], v[80:83], v[108:111], v[44:47]
	v_mfma_f32_16x16x32_bf16 v[40:43], v[80:83], v[112:115], v[40:43]
	v_mfma_f32_16x16x32_bf16 v[36:39], v[80:83], v[116:119], v[36:39]
	v_mfma_f32_16x16x32_bf16 v[32:35], v[80:83], v[120:123], v[32:35]
	v_mfma_f32_16x16x32_bf16 v[28:31], v[84:87], v[108:111], v[28:31]
	v_mfma_f32_16x16x32_bf16 v[24:27], v[84:87], v[112:115], v[24:27]
	v_mfma_f32_16x16x32_bf16 v[20:23], v[84:87], v[116:119], v[20:23]
	v_mfma_f32_16x16x32_bf16 v[16:19], v[84:87], v[120:123], v[16:19]
	v_mfma_f32_16x16x32_bf16 v[12:15], v[88:91], v[108:111], v[12:15]
	v_mfma_f32_16x16x32_bf16 v[8:11], v[88:91], v[112:115], v[8:11]
	v_mfma_f32_16x16x32_bf16 v[4:7], v[88:91], v[116:119], v[4:7]
	v_mfma_f32_16x16x32_bf16 v[0:3], v[88:91], v[120:123], v[0:3]
	ds_read_b128 v[108:111], v151 offset:32768
	ds_read_b128 v[112:115], v151 offset:34816
	ds_read_b128 v[116:119], v151 offset:36864
	ds_read_b128 v[120:123], v151 offset:38912
	s_waitcnt lgkmcnt(0)
	v_mfma_f32_16x16x32_bf16 v[60:63], v[92:95], v[108:111], v[60:63]
	v_mfma_f32_16x16x32_bf16 v[56:59], v[92:95], v[112:115], v[56:59]
	v_mfma_f32_16x16x32_bf16 v[52:55], v[92:95], v[116:119], v[52:55]
	v_mfma_f32_16x16x32_bf16 v[48:51], v[92:95], v[120:123], v[48:51]
	v_mfma_f32_16x16x32_bf16 v[44:47], v[96:99], v[108:111], v[44:47]
	v_mfma_f32_16x16x32_bf16 v[40:43], v[96:99], v[112:115], v[40:43]
	v_mfma_f32_16x16x32_bf16 v[36:39], v[96:99], v[116:119], v[36:39]
	v_mfma_f32_16x16x32_bf16 v[32:35], v[96:99], v[120:123], v[32:35]
	v_mfma_f32_16x16x32_bf16 v[28:31], v[100:103], v[108:111], v[28:31]
	v_mfma_f32_16x16x32_bf16 v[24:27], v[100:103], v[112:115], v[24:27]
	v_mfma_f32_16x16x32_bf16 v[20:23], v[100:103], v[116:119], v[20:23]
	v_mfma_f32_16x16x32_bf16 v[16:19], v[100:103], v[120:123], v[16:19]
	v_mfma_f32_16x16x32_bf16 v[12:15], v[104:107], v[108:111], v[12:15]
	v_mfma_f32_16x16x32_bf16 v[8:11], v[104:107], v[112:115], v[8:11]
	v_mfma_f32_16x16x32_bf16 v[4:7], v[104:107], v[116:119], v[4:7]
	v_mfma_f32_16x16x32_bf16 v[0:3], v[104:107], v[120:123], v[0:3]
	s_waitcnt vmcnt(0)
	s_barrier
	ds_read_b128 v[108:111], v150 offset:49152
	ds_read_b128 v[112:115], v150 offset:51200
	ds_read_b128 v[116:119], v150 offset:53248
	ds_read_b128 v[120:123], v150 offset:55296
	s_waitcnt lgkmcnt(0)
	v_mfma_f32_16x16x32_bf16 v[202:205], v[76:79], v[108:111], v[202:205]
	v_mfma_f32_16x16x32_bf16 v[206:209], v[76:79], v[112:115], v[206:209]
	v_mfma_f32_16x16x32_bf16 v[210:213], v[76:79], v[116:119], v[210:213]
	v_mfma_f32_16x16x32_bf16 v[214:217], v[76:79], v[120:123], v[214:217]
	v_mfma_f32_16x16x32_bf16 v[218:221], v[80:83], v[108:111], v[218:221]
	v_mfma_f32_16x16x32_bf16 v[222:225], v[80:83], v[112:115], v[222:225]
	v_mfma_f32_16x16x32_bf16 v[226:229], v[80:83], v[116:119], v[226:229]
	v_mfma_f32_16x16x32_bf16 v[230:233], v[80:83], v[120:123], v[230:233]
	v_mfma_f32_16x16x32_bf16 v[234:237], v[84:87], v[108:111], v[234:237]
	v_mfma_f32_16x16x32_bf16 v[238:241], v[84:87], v[112:115], v[238:241]
	v_mfma_f32_16x16x32_bf16 v[248:251], v[84:87], v[116:119], v[248:251]
	v_mfma_f32_16x16x32_bf16 v[252:255], v[84:87], v[120:123], v[252:255]
	v_mfma_f32_16x16x32_bf16 v[124:127], v[88:91], v[108:111], v[124:127]
	v_mfma_f32_16x16x32_bf16 v[128:131], v[88:91], v[112:115], v[128:131]
	v_mfma_f32_16x16x32_bf16 v[132:135], v[88:91], v[116:119], v[132:135]
	v_mfma_f32_16x16x32_bf16 v[146:149], v[88:91], v[120:123], v[146:149]
	ds_read_b128 v[108:111], v151 offset:49152
	ds_read_b128 v[112:115], v151 offset:51200
	ds_read_b128 v[116:119], v151 offset:53248
	ds_read_b128 v[120:123], v151 offset:55296
	s_waitcnt lgkmcnt(0)
	v_mfma_f32_16x16x32_bf16 v[202:205], v[92:95], v[108:111], v[202:205]
	v_mfma_f32_16x16x32_bf16 v[206:209], v[92:95], v[112:115], v[206:209]
	v_mfma_f32_16x16x32_bf16 v[210:213], v[92:95], v[116:119], v[210:213]
	v_mfma_f32_16x16x32_bf16 v[214:217], v[92:95], v[120:123], v[214:217]
	v_mfma_f32_16x16x32_bf16 v[218:221], v[96:99], v[108:111], v[218:221]
	v_mfma_f32_16x16x32_bf16 v[222:225], v[96:99], v[112:115], v[222:225]
	v_mfma_f32_16x16x32_bf16 v[226:229], v[96:99], v[116:119], v[226:229]
	v_mfma_f32_16x16x32_bf16 v[230:233], v[96:99], v[120:123], v[230:233]
	v_mfma_f32_16x16x32_bf16 v[234:237], v[100:103], v[108:111], v[234:237]
	v_mfma_f32_16x16x32_bf16 v[238:241], v[100:103], v[112:115], v[238:241]
	v_mfma_f32_16x16x32_bf16 v[248:251], v[100:103], v[116:119], v[248:251]
	v_mfma_f32_16x16x32_bf16 v[252:255], v[100:103], v[120:123], v[252:255]
	v_mfma_f32_16x16x32_bf16 v[124:127], v[104:107], v[108:111], v[124:127]
	v_mfma_f32_16x16x32_bf16 v[128:131], v[104:107], v[112:115], v[128:131]
	v_mfma_f32_16x16x32_bf16 v[132:135], v[104:107], v[116:119], v[132:135]
	v_mfma_f32_16x16x32_bf16 v[146:149], v[104:107], v[120:123], v[146:149]
	s_branch ff1g_epi
ff1g_odd:
	v_mov_b32_e32 v60, v202
	v_mov_b32_e32 v61, v203
	v_mov_b32_e32 v62, v204
	v_mov_b32_e32 v63, v205
	v_mov_b32_e32 v56, v206
	v_mov_b32_e32 v57, v207
	v_mov_b32_e32 v58, v208
	v_mov_b32_e32 v59, v209
	v_mov_b32_e32 v52, v210
	v_mov_b32_e32 v53, v211
	v_mov_b32_e32 v54, v212
	v_mov_b32_e32 v55, v213
	v_mov_b32_e32 v48, v214
	v_mov_b32_e32 v49, v215
	v_mov_b32_e32 v50, v216
	v_mov_b32_e32 v51, v217
	v_mov_b32_e32 v44, v218
	v_mov_b32_e32 v45, v219
	v_mov_b32_e32 v46, v220
	v_mov_b32_e32 v47, v221
	v_mov_b32_e32 v40, v222
	v_mov_b32_e32 v41, v223
	v_mov_b32_e32 v42, v224
	v_mov_b32_e32 v43, v225
	v_mov_b32_e32 v36, v226
	v_mov_b32_e32 v37, v227
	v_mov_b32_e32 v38, v228
	v_mov_b32_e32 v39, v229
	v_mov_b32_e32 v32, v230
	v_mov_b32_e32 v33, v231
	v_mov_b32_e32 v34, v232
	v_mov_b32_e32 v35, v233
	v_mov_b32_e32 v28, v234
	v_mov_b32_e32 v29, v235
	v_mov_b32_e32 v30, v236
	v_mov_b32_e32 v31, v237
	v_mov_b32_e32 v24, v238
	v_mov_b32_e32 v25, v239
	v_mov_b32_e32 v26, v240
	v_mov_b32_e32 v27, v241
	v_mov_b32_e32 v20, v248
	v_mov_b32_e32 v21, v249
	v_mov_b32_e32 v22, v250
	v_mov_b32_e32 v23, v251
	v_mov_b32_e32 v16, v252
	v_mov_b32_e32 v17, v253
	v_mov_b32_e32 v18, v254
	v_mov_b32_e32 v19, v255
	v_mov_b32_e32 v12, v124
	v_mov_b32_e32 v13, v125
	v_mov_b32_e32 v14, v126
	v_mov_b32_e32 v15, v127
	v_mov_b32_e32 v8, v128
	v_mov_b32_e32 v9, v129
	v_mov_b32_e32 v10, v130
	v_mov_b32_e32 v11, v131
	v_mov_b32_e32 v4, v132
	v_mov_b32_e32 v5, v133
	v_mov_b32_e32 v6, v134
	v_mov_b32_e32 v7, v135
	v_mov_b32_e32 v0, v146
	v_mov_b32_e32 v1, v147
	v_mov_b32_e32 v2, v148
	v_mov_b32_e32 v3, v149
ff1g_epi:
	s_movk_i32 s4, 0x2400
	v_max_f32_e32 v60, v60, v60
	v_max_f32_e32 v56, v56, v56
	v_max_f32_e32 v52, v52, v52
	v_max_f32_e32 v48, v48, v48
	v_max_f32_e32 v44, v44, v44
	v_max_f32_e32 v40, v40, v40
	v_max_f32_e32 v36, v36, v36
	v_max_f32_e32 v32, v32, v32
	v_max_f32_e32 v28, v28, v28
	v_max_f32_e32 v24, v24, v24
	v_max_f32_e32 v20, v20, v20
	v_max_f32_e32 v16, v16, v16
	v_max_f32_e32 v12, v12, v12
	v_max_f32_e32 v8, v8, v8
	v_max_f32_e32 v4, v4, v4
	v_max_f32_e32 v0, v0, v0
	v_mul_lo_u32 v64, v72, s4
	v_max_f32_e32 v60, 0, v60
	v_max_f32_e32 v61, v61, v61
	v_max_f32_e32 v56, 0, v56
	v_max_f32_e32 v57, v57, v57
	v_max_f32_e32 v52, 0, v52
	v_max_f32_e32 v53, v53, v53
	v_max_f32_e32 v48, 0, v48
	v_max_f32_e32 v49, v49, v49
	v_max_f32_e32 v44, 0, v44
	v_max_f32_e32 v45, v45, v45
	v_max_f32_e32 v40, 0, v40
	v_max_f32_e32 v41, v41, v41
	v_max_f32_e32 v36, 0, v36
	v_max_f32_e32 v37, v37, v37
	v_max_f32_e32 v32, 0, v32
	v_max_f32_e32 v33, v33, v33
	v_max_f32_e32 v28, 0, v28
	v_max_f32_e32 v29, v29, v29
	v_max_f32_e32 v24, 0, v24
	v_max_f32_e32 v25, v25, v25
	v_max_f32_e32 v20, 0, v20
	v_max_f32_e32 v21, v21, v21
	v_max_f32_e32 v16, 0, v16
	v_max_f32_e32 v17, v17, v17
	v_max_f32_e32 v12, 0, v12
	v_max_f32_e32 v13, v13, v13
	v_max_f32_e32 v8, 0, v8
	v_max_f32_e32 v9, v9, v9
	v_max_f32_e32 v4, 0, v4
	v_max_f32_e32 v5, v5, v5
	v_max_f32_e32 v0, 0, v0
	v_max_f32_e32 v1, v1, v1
	v_lshl_or_b32 v65, v73, 1, v64
	v_mul_f32_e32 v60, v60, v60
	v_max_f32_e32 v61, 0, v61
	v_max_f32_e32 v62, v62, v62
	s_movk_i32 s4, 0x240
	v_mul_f32_e32 v56, v56, v56
	v_max_f32_e32 v57, 0, v57
	v_max_f32_e32 v58, v58, v58
	v_mul_f32_e32 v52, v52, v52
	v_max_f32_e32 v53, 0, v53
	v_max_f32_e32 v54, v54, v54
	v_mul_f32_e32 v48, v48, v48
	v_max_f32_e32 v49, 0, v49
	v_max_f32_e32 v50, v50, v50
	v_mul_f32_e32 v44, v44, v44
	v_max_f32_e32 v45, 0, v45
	v_max_f32_e32 v46, v46, v46
	v_mul_f32_e32 v40, v40, v40
	v_max_f32_e32 v41, 0, v41
	v_max_f32_e32 v42, v42, v42
	v_mul_f32_e32 v36, v36, v36
	v_max_f32_e32 v37, 0, v37
	v_max_f32_e32 v38, v38, v38
	v_mul_f32_e32 v32, v32, v32
	v_max_f32_e32 v33, 0, v33
	v_max_f32_e32 v34, v34, v34
	v_mul_f32_e32 v28, v28, v28
	v_max_f32_e32 v29, 0, v29
	v_max_f32_e32 v30, v30, v30
	v_mul_f32_e32 v24, v24, v24
	v_max_f32_e32 v25, 0, v25
	v_max_f32_e32 v26, v26, v26
	v_mul_f32_e32 v20, v20, v20
	v_max_f32_e32 v21, 0, v21
	v_max_f32_e32 v22, v22, v22
	v_mul_f32_e32 v16, v16, v16
	v_max_f32_e32 v17, 0, v17
	v_max_f32_e32 v18, v18, v18
	v_mul_f32_e32 v12, v12, v12
	v_max_f32_e32 v13, 0, v13
	v_max_f32_e32 v14, v14, v14
	v_mul_f32_e32 v8, v8, v8
	v_max_f32_e32 v9, 0, v9
	v_max_f32_e32 v10, v10, v10
	v_mul_f32_e32 v4, v4, v4
	v_max_f32_e32 v5, 0, v5
	v_max_f32_e32 v6, v6, v6
	v_mul_f32_e32 v0, v0, v0
	v_max_f32_e32 v1, 0, v1
	v_max_f32_e32 v2, v2, v2
	v_mul_f32_e32 v61, v61, v61
	v_max_f32_e32 v62, 0, v62
	v_max_f32_e32 v63, v63, v63
	v_cvt_pk_bf16_f32 v60, v60, s0
	v_mad_u32_u24 v65, v71, s4, v65
	v_mul_f32_e32 v57, v57, v57
	v_max_f32_e32 v58, 0, v58
	v_max_f32_e32 v59, v59, v59
	v_cvt_pk_bf16_f32 v56, v56, s0
	v_mul_f32_e32 v53, v53, v53
	v_max_f32_e32 v54, 0, v54
	v_max_f32_e32 v55, v55, v55
	v_cvt_pk_bf16_f32 v52, v52, s0
	v_mul_f32_e32 v49, v49, v49
	v_max_f32_e32 v50, 0, v50
	v_max_f32_e32 v51, v51, v51
	v_cvt_pk_bf16_f32 v48, v48, s0
	v_mul_f32_e32 v45, v45, v45
	v_max_f32_e32 v46, 0, v46
	v_max_f32_e32 v47, v47, v47
	v_cvt_pk_bf16_f32 v44, v44, s0
	v_mul_f32_e32 v41, v41, v41
	v_max_f32_e32 v42, 0, v42
	v_max_f32_e32 v43, v43, v43
	v_cvt_pk_bf16_f32 v40, v40, s0
	v_mul_f32_e32 v37, v37, v37
	v_max_f32_e32 v38, 0, v38
	v_max_f32_e32 v39, v39, v39
	v_cvt_pk_bf16_f32 v36, v36, s0
	v_mul_f32_e32 v33, v33, v33
	v_max_f32_e32 v34, 0, v34
	v_max_f32_e32 v35, v35, v35
	v_cvt_pk_bf16_f32 v32, v32, s0
	v_mul_f32_e32 v29, v29, v29
	v_max_f32_e32 v30, 0, v30
	v_max_f32_e32 v31, v31, v31
	v_cvt_pk_bf16_f32 v28, v28, s0
	v_mul_f32_e32 v25, v25, v25
	v_max_f32_e32 v26, 0, v26
	v_max_f32_e32 v27, v27, v27
	v_cvt_pk_bf16_f32 v24, v24, s0
	v_mul_f32_e32 v21, v21, v21
	v_max_f32_e32 v22, 0, v22
	v_max_f32_e32 v23, v23, v23
	v_cvt_pk_bf16_f32 v20, v20, s0
	v_mul_f32_e32 v17, v17, v17
	v_max_f32_e32 v18, 0, v18
	v_max_f32_e32 v19, v19, v19
	v_cvt_pk_bf16_f32 v16, v16, s0
	v_mul_f32_e32 v13, v13, v13
	v_max_f32_e32 v14, 0, v14
	v_max_f32_e32 v15, v15, v15
	v_cvt_pk_bf16_f32 v12, v12, s0
	v_mul_f32_e32 v9, v9, v9
	v_max_f32_e32 v10, 0, v10
	v_max_f32_e32 v11, v11, v11
	v_cvt_pk_bf16_f32 v8, v8, s0
	v_mul_f32_e32 v5, v5, v5
	v_max_f32_e32 v6, 0, v6
	v_max_f32_e32 v7, v7, v7
	v_cvt_pk_bf16_f32 v4, v4, s0
	v_mul_f32_e32 v1, v1, v1
	v_max_f32_e32 v2, 0, v2
	v_max_f32_e32 v3, v3, v3
	v_cvt_pk_bf16_f32 v0, v0, s0
	s_waitcnt vmcnt(0)
	s_barrier
	v_mul_f32_e32 v62, v62, v62
	v_max_f32_e32 v63, 0, v63
	ds_write_b16 v65, v60
	v_cvt_pk_bf16_f32 v60, v61, s0
	v_mul_f32_e32 v58, v58, v58
	v_max_f32_e32 v59, 0, v59
	ds_write_b16 v65, v56 offset:32
	v_cvt_pk_bf16_f32 v56, v57, s0
	v_mul_f32_e32 v54, v54, v54
	v_max_f32_e32 v55, 0, v55
	ds_write_b16 v65, v52 offset:64
	v_cvt_pk_bf16_f32 v52, v53, s0
	v_mul_f32_e32 v50, v50, v50
	v_max_f32_e32 v51, 0, v51
	ds_write_b16 v65, v48 offset:96
	v_cvt_pk_bf16_f32 v48, v49, s0
	v_mul_f32_e32 v46, v46, v46
	v_max_f32_e32 v47, 0, v47
	ds_write_b16 v65, v44 offset:2304
	v_cvt_pk_bf16_f32 v44, v45, s0
	v_mul_f32_e32 v42, v42, v42
	v_max_f32_e32 v43, 0, v43
	ds_write_b16 v65, v40 offset:2336
	v_cvt_pk_bf16_f32 v40, v41, s0
	v_mul_f32_e32 v38, v38, v38
	v_max_f32_e32 v39, 0, v39
	ds_write_b16 v65, v36 offset:2368
	v_cvt_pk_bf16_f32 v36, v37, s0
	v_mul_f32_e32 v34, v34, v34
	v_max_f32_e32 v35, 0, v35
	ds_write_b16 v65, v32 offset:2400
	v_cvt_pk_bf16_f32 v32, v33, s0
	v_mul_f32_e32 v30, v30, v30
	v_max_f32_e32 v31, 0, v31
	ds_write_b16 v65, v28 offset:4608
	v_cvt_pk_bf16_f32 v28, v29, s0
	v_mul_f32_e32 v26, v26, v26
	v_max_f32_e32 v27, 0, v27
	ds_write_b16 v65, v24 offset:4640
	v_cvt_pk_bf16_f32 v24, v25, s0
	v_mul_f32_e32 v22, v22, v22
	v_max_f32_e32 v23, 0, v23
	ds_write_b16 v65, v20 offset:4672
	v_cvt_pk_bf16_f32 v20, v21, s0
	v_mul_f32_e32 v18, v18, v18
	v_max_f32_e32 v19, 0, v19
	ds_write_b16 v65, v16 offset:4704
	v_cvt_pk_bf16_f32 v16, v17, s0
	v_mul_f32_e32 v14, v14, v14
	v_max_f32_e32 v15, 0, v15
	ds_write_b16 v65, v12 offset:6912
	v_cvt_pk_bf16_f32 v12, v13, s0
	v_mul_f32_e32 v10, v10, v10
	v_max_f32_e32 v11, 0, v11
	ds_write_b16 v65, v8 offset:6944
	v_cvt_pk_bf16_f32 v8, v9, s0
	v_mul_f32_e32 v6, v6, v6
	v_max_f32_e32 v7, 0, v7
	ds_write_b16 v65, v4 offset:6976
	v_cvt_pk_bf16_f32 v4, v5, s0
	v_mul_f32_e32 v2, v2, v2
	v_max_f32_e32 v3, 0, v3
	ds_write_b16 v65, v0 offset:7008
	v_cvt_pk_bf16_f32 v0, v1, s0
	v_mul_f32_e32 v63, v63, v63
	ds_write_b16 v65, v60 offset:144
	v_cvt_pk_bf16_f32 v60, v62, s0
	v_mul_f32_e32 v59, v59, v59
	ds_write_b16 v65, v56 offset:176
	v_cvt_pk_bf16_f32 v56, v58, s0
	v_mul_f32_e32 v55, v55, v55
	ds_write_b16 v65, v52 offset:208
	v_cvt_pk_bf16_f32 v52, v54, s0
	v_mul_f32_e32 v51, v51, v51
	ds_write_b16 v65, v48 offset:240
	v_cvt_pk_bf16_f32 v48, v50, s0
	v_mul_f32_e32 v47, v47, v47
	ds_write_b16 v65, v44 offset:2448
	v_cvt_pk_bf16_f32 v44, v46, s0
	v_mul_f32_e32 v43, v43, v43
	ds_write_b16 v65, v40 offset:2480
	v_cvt_pk_bf16_f32 v40, v42, s0
	v_mul_f32_e32 v39, v39, v39
	ds_write_b16 v65, v36 offset:2512
	v_cvt_pk_bf16_f32 v36, v38, s0
	v_mul_f32_e32 v35, v35, v35
	ds_write_b16 v65, v32 offset:2544
	v_cvt_pk_bf16_f32 v32, v34, s0
	v_mul_f32_e32 v31, v31, v31
	ds_write_b16 v65, v28 offset:4752
	v_cvt_pk_bf16_f32 v28, v30, s0
	v_mul_f32_e32 v27, v27, v27
	ds_write_b16 v65, v24 offset:4784
	v_cvt_pk_bf16_f32 v24, v26, s0
	v_mul_f32_e32 v23, v23, v23
	ds_write_b16 v65, v20 offset:4816
	v_cvt_pk_bf16_f32 v20, v22, s0
	v_mul_f32_e32 v19, v19, v19
	ds_write_b16 v65, v16 offset:4848
	v_cvt_pk_bf16_f32 v16, v18, s0
	v_mul_f32_e32 v15, v15, v15
	ds_write_b16 v65, v12 offset:7056
	v_cvt_pk_bf16_f32 v12, v14, s0
	v_mul_f32_e32 v11, v11, v11
	ds_write_b16 v65, v8 offset:7088
	v_cvt_pk_bf16_f32 v8, v10, s0
	v_mul_f32_e32 v7, v7, v7
	ds_write_b16 v65, v4 offset:7120
	v_cvt_pk_bf16_f32 v4, v6, s0
	v_mul_f32_e32 v3, v3, v3
	ds_write_b16 v65, v0 offset:7152
	v_cvt_pk_bf16_f32 v0, v2, s0
	v_add_u32_e32 v5, s1, v70
	s_ashr_i32 s1, s0, 31
	v_readlane_b32 s36, v246, 25
	ds_write_b16 v65, v60 offset:288
	v_cvt_pk_bf16_f32 v60, v63, s0
	ds_write_b16 v65, v56 offset:320
	v_cvt_pk_bf16_f32 v56, v59, s0
	ds_write_b16 v65, v52 offset:352
	v_cvt_pk_bf16_f32 v52, v55, s0
	ds_write_b16 v65, v48 offset:384
	v_cvt_pk_bf16_f32 v48, v51, s0
	ds_write_b16 v65, v44 offset:2592
	v_cvt_pk_bf16_f32 v44, v47, s0
	ds_write_b16 v65, v40 offset:2624
	v_cvt_pk_bf16_f32 v40, v43, s0
	ds_write_b16 v65, v36 offset:2656
	v_cvt_pk_bf16_f32 v36, v39, s0
	ds_write_b16 v65, v32 offset:2688
	v_cvt_pk_bf16_f32 v32, v35, s0
	ds_write_b16 v65, v28 offset:4896
	v_cvt_pk_bf16_f32 v28, v31, s0
	ds_write_b16 v65, v24 offset:4928
	v_cvt_pk_bf16_f32 v24, v27, s0
	ds_write_b16 v65, v20 offset:4960
	v_cvt_pk_bf16_f32 v20, v23, s0
	ds_write_b16 v65, v16 offset:4992
	v_cvt_pk_bf16_f32 v16, v19, s0
	ds_write_b16 v65, v12 offset:7200
	v_cvt_pk_bf16_f32 v12, v15, s0
	ds_write_b16 v65, v8 offset:7232
	v_cvt_pk_bf16_f32 v8, v11, s0
	ds_write_b16 v65, v4 offset:7264
	v_cvt_pk_bf16_f32 v4, v7, s0
	ds_write_b16 v65, v0 offset:7296
	v_cvt_pk_bf16_f32 v0, v3, s0
	s_lshl_b64 s[0:1], s[0:1], 1
	v_readlane_b32 s38, v246, 27
	ds_write_b16 v65, v0 offset:7440
	v_lshlrev_b32_e32 v0, 4, v69
	v_readlane_b32 s39, v246, 28
	s_add_u32 s0, s38, s0
	v_and_b32_e32 v0, 0x70, v0
	s_addc_u32 s1, s39, s1
	v_and_b32_e32 v136, 64, v69
	v_lshlrev_b32_e32 v136, 1, v136
	ds_write_b16 v65, v4 offset:7408
	v_or_b32_e32 v4, v64, v0
	v_lshl_add_u64 v[2:3], s[0:1], 0, v[136:137]
	s_movk_i32 s0, 0x90
	ds_write_b16 v65, v60 offset:432
	ds_write_b16 v65, v56 offset:464
	ds_write_b16 v65, v52 offset:496
	ds_write_b16 v65, v48 offset:528
	ds_write_b16 v65, v44 offset:2736
	ds_write_b16 v65, v40 offset:2768
	ds_write_b16 v65, v36 offset:2800
	ds_write_b16 v65, v32 offset:2832
	ds_write_b16 v65, v28 offset:5040
	ds_write_b16 v65, v24 offset:5072
	ds_write_b16 v65, v20 offset:5104
	ds_write_b16 v65, v16 offset:5136
	ds_write_b16 v65, v12 offset:7344
	ds_write_b16 v65, v8 offset:7376
	v_mov_b32_e32 v1, v137
	v_mad_u32_u24 v12, v68, s0, v4
	v_lshl_add_u64 v[8:9], v[2:3], 0, v[0:1]
	ds_read_b128 v[0:3], v12
	v_or_b32_e32 v13, v5, v68
	ds_read_b128 v[4:7], v12 offset:1152
	s_movk_i32 s4, 0x2080
	v_mad_i64_i32 v[10:11], s[0:1], v13, s4, v[8:9]
	s_waitcnt lgkmcnt(1)
	global_store_dwordx4 v[10:11], v[0:3], off
	s_add_i32 s6, s6, 1
	s_movk_i32 s36, 0x880
	v_or_b32_e32 v0, 8, v13
	v_mad_i64_i32 v[0:1], s[0:1], v0, s4, v[8:9]
	s_waitcnt lgkmcnt(0)
	global_store_dwordx4 v[0:1], v[4:7], off
	ds_read_b128 v[0:3], v12 offset:2304
	v_readlane_b32 s37, v246, 26
	v_or_b32_e32 v4, 16, v13
	v_mad_i64_i32 v[10:11], s[0:1], v4, s4, v[8:9]
	ds_read_b128 v[4:7], v12 offset:3456
	s_waitcnt lgkmcnt(1)
	global_store_dwordx4 v[10:11], v[0:3], off
	v_readlane_b32 s40, v246, 29
	v_readlane_b32 s41, v246, 30
	v_or_b32_e32 v0, 24, v13
	v_mad_i64_i32 v[0:1], s[0:1], v0, s4, v[8:9]
	s_waitcnt lgkmcnt(0)
	global_store_dwordx4 v[0:1], v[4:7], off
	ds_read_b128 v[0:3], v12 offset:4608
	v_readlane_b32 s42, v246, 31
	v_or_b32_e32 v4, 32, v13
	v_mad_i64_i32 v[10:11], s[0:1], v4, s4, v[8:9]
	ds_read_b128 v[4:7], v12 offset:5760
	s_waitcnt lgkmcnt(1)
	global_store_dwordx4 v[10:11], v[0:3], off
	v_readlane_b32 s43, v246, 32
	v_readlane_b32 s44, v246, 33
	v_or_b32_e32 v0, 40, v13
	v_mad_i64_i32 v[0:1], s[0:1], v0, s4, v[8:9]
	s_waitcnt lgkmcnt(0)
	global_store_dwordx4 v[0:1], v[4:7], off
	ds_read_b128 v[0:3], v12 offset:6912
	v_readlane_b32 s45, v246, 34
	v_or_b32_e32 v4, 48, v13
	v_mad_i64_i32 v[10:11], s[0:1], v4, s4, v[8:9]
	ds_read_b128 v[4:7], v12 offset:8064
	s_waitcnt lgkmcnt(1)
	global_store_dwordx4 v[10:11], v[0:3], off
	v_readlane_b32 s46, v246, 35
	v_readlane_b32 s47, v246, 36
	v_or_b32_e32 v0, 56, v13
	v_mad_i64_i32 v[0:1], s[0:1], v0, s4, v[8:9]
	s_mov_b64 s[4:5], 0
	v_readlane_b32 s48, v246, 37
	v_readlane_b32 s49, v246, 38
	v_readlane_b32 s50, v246, 39
	v_readlane_b32 s51, v246, 40
	s_waitcnt lgkmcnt(0)
	global_store_dwordx4 v[0:1], v[4:7], off
	s_barrier
	s_branch .LBB0_141
